# pipelined double-buffered window shift-copy loops + phase-0 weight-transpose loads issued back to back
# speedup vs baseline: 1.0210x; 1.0210x over previous
.LBB0_53:
	v_mul_hi_i32 v0, v8, s18
	v_lshrrev_b32_e32 v1, 31, v0
	v_ashrrev_i32_e32 v0, 10, v0
	v_add_u32_e32 v0, v0, v1
	v_mul_i32_i24_e32 v1, 0xc80, v0
	v_sub_u32_e32 v2, v8, v1
	v_readlane_b32 s52, v255, 12
	v_lshlrev_b32_e32 v0, 3, v0
	v_ashrrev_i32_e32 v3, 31, v2
	v_readlane_b32 s53, v255, 13
	v_mul_hi_i32_i24_e32 v7, 0x3200, v0
	v_mul_i32_i24_e32 v6, 0x3200, v0
	v_lshl_add_u64 v[4:5], v[2:3], 2, s[52:53]
	v_lshl_add_u64 v[6:7], v[4:5], 0, v[6:7]
	global_load_dword v9, v[6:7], off
	v_ashrrev_i32_e32 v1, 31, v0
	s_and_b64 vcc, exec, s[0:1]
	v_lshl_add_u64 v[6:7], v[0:1], 2, s[90:91]
	v_readlane_b32 s54, v255, 14
	v_readlane_b32 s55, v255, 15
	v_readlane_b32 s56, v255, 16
	v_readlane_b32 s57, v255, 17
	v_readlane_b32 s58, v255, 18
	v_readlane_b32 s59, v255, 19
	v_readlane_b32 s60, v255, 20
	v_readlane_b32 s61, v255, 21
	v_readlane_b32 s62, v255, 22
	v_readlane_b32 s63, v255, 23
	v_readlane_b32 s64, v255, 24
	v_readlane_b32 s65, v255, 25
	v_readlane_b32 s66, v255, 26
	v_readlane_b32 s67, v255, 27
.LBB0_55:
	v_or_b32_e32 v10, 1, v0
	v_mul_hi_i32_i24_e32 v11, 0x3200, v10
	v_mul_i32_i24_e32 v10, 0x3200, v10
	v_lshl_add_u64 v[10:11], v[4:5], 0, v[10:11]
	global_load_dword v10, v[10:11], off
	s_and_b64 vcc, exec, s[0:1]
.LBB0_57:
	v_or_b32_e32 v11, 2, v0
	v_mul_hi_i32_i24_e32 v13, 0x3200, v11
	v_mul_i32_i24_e32 v12, 0x3200, v11
	v_lshl_add_u64 v[12:13], v[4:5], 0, v[12:13]
	global_load_dword v11, v[12:13], off
	s_and_b64 vcc, exec, s[0:1]
.LBB0_59:
	v_or_b32_e32 v12, 3, v0
	v_mul_hi_i32_i24_e32 v13, 0x3200, v12
	v_mul_i32_i24_e32 v12, 0x3200, v12
	v_lshl_add_u64 v[12:13], v[4:5], 0, v[12:13]
	global_load_dword v12, v[12:13], off
	s_and_b64 vcc, exec, s[0:1]
.LBB0_61:
	v_or_b32_e32 v13, 4, v0
	v_mul_hi_i32_i24_e32 v15, 0x3200, v13
	v_mul_i32_i24_e32 v14, 0x3200, v13
	v_lshl_add_u64 v[14:15], v[4:5], 0, v[14:15]
	global_load_dword v13, v[14:15], off
	s_and_b64 vcc, exec, s[0:1]
.LBB0_63:
	v_or_b32_e32 v14, 5, v0
	v_mul_hi_i32_i24_e32 v15, 0x3200, v14
	v_mul_i32_i24_e32 v14, 0x3200, v14
	v_lshl_add_u64 v[14:15], v[4:5], 0, v[14:15]
	global_load_dword v14, v[14:15], off
	s_and_b64 vcc, exec, s[0:1]
.LBB0_65:
	v_or_b32_e32 v15, 6, v0
	v_mul_hi_i32_i24_e32 v17, 0x3200, v15
	v_mul_i32_i24_e32 v16, 0x3200, v15
	v_lshl_add_u64 v[16:17], v[4:5], 0, v[16:17]
	global_load_dword v15, v[16:17], off
	s_and_b64 vcc, exec, s[0:1]
.LBB0_67:
	v_or_b32_e32 v16, 7, v0
	v_mul_hi_i32_i24_e32 v17, 0x3200, v16
	v_mul_i32_i24_e32 v16, 0x3200, v16
	v_lshl_add_u64 v[4:5], v[4:5], 0, v[16:17]
	global_load_dword v4, v[4:5], off
	s_and_b64 vcc, exec, s[0:1]
	s_cbranch_vccnz .LBB0_52
	global_load_dwordx4 v[30:33], v[6:7], off
	global_load_dwordx4 v[34:37], v[6:7], off offset:16
	s_waitcnt vmcnt(0)
	v_mul_f32_e32 v9, v9, v30
	v_mul_f32_e32 v10, v10, v31
	v_mul_f32_e32 v11, v11, v32
	v_mul_f32_e32 v12, v12, v33
	v_mul_f32_e32 v13, v13, v34
	v_mul_f32_e32 v14, v14, v35
	v_mul_f32_e32 v15, v15, v36
	v_mul_f32_e32 v4, v4, v37
	s_branch .LBB0_52

.LBB0_78:
	v_ashrrev_i32_e32 v0, 31, v8
	v_lshrrev_b32_e32 v0, 23, v0
	v_add_u32_e32 v0, v8, v0
	v_ashrrev_i32_e32 v0, 9, v0
	v_mul_i32_i24_e32 v1, 0x200, v0
	v_sub_u32_e32 v2, v8, v1
	v_lshlrev_b32_e32 v0, 3, v0
	v_readlane_b32 s20, v255, 0
	v_ashrrev_i32_e32 v3, 31, v2
	v_readlane_b32 s21, v255, 1
	v_ashrrev_i32_e32 v1, 31, v0
	v_lshlrev_b64 v[6:7], 11, v[0:1]
	v_lshl_add_u64 v[4:5], v[2:3], 2, s[20:21]
	v_lshl_add_u64 v[6:7], v[4:5], 0, v[6:7]
	global_load_dword v9, v[6:7], off
	v_readlane_b32 s52, v255, 12
	v_readlane_b32 s66, v255, 26
	v_readlane_b32 s67, v255, 27
	s_and_b64 vcc, exec, s[0:1]
	v_readlane_b32 s22, v255, 2
	v_lshl_add_u64 v[6:7], v[0:1], 2, s[66:67]
	v_readlane_b32 s23, v255, 3
	v_readlane_b32 s24, v255, 4
	v_readlane_b32 s25, v255, 5
	v_readlane_b32 s26, v255, 6
	v_readlane_b32 s27, v255, 7
	v_readlane_b32 s53, v255, 13
	v_readlane_b32 s54, v255, 14
	v_readlane_b32 s55, v255, 15
	v_readlane_b32 s56, v255, 16
	v_readlane_b32 s57, v255, 17
	v_readlane_b32 s58, v255, 18
	v_readlane_b32 s59, v255, 19
	v_readlane_b32 s60, v255, 20
	v_readlane_b32 s61, v255, 21
	v_readlane_b32 s62, v255, 22
	v_readlane_b32 s63, v255, 23
	v_readlane_b32 s64, v255, 24
	v_readlane_b32 s65, v255, 25
.LBB0_80:
	v_or_b32_e32 v10, 1, v0
	v_ashrrev_i32_e32 v11, 31, v10
	v_lshlrev_b64 v[10:11], 11, v[10:11]
	v_lshl_add_u64 v[10:11], v[4:5], 0, v[10:11]
	global_load_dword v10, v[10:11], off
	s_and_b64 vcc, exec, s[0:1]
.LBB0_82:
	v_or_b32_e32 v12, 2, v0
	v_ashrrev_i32_e32 v13, 31, v12
	v_lshlrev_b64 v[12:13], 11, v[12:13]
	v_lshl_add_u64 v[12:13], v[4:5], 0, v[12:13]
	global_load_dword v11, v[12:13], off
	s_and_b64 vcc, exec, s[0:1]
.LBB0_84:
	v_or_b32_e32 v12, 3, v0
	v_ashrrev_i32_e32 v13, 31, v12
	v_lshlrev_b64 v[12:13], 11, v[12:13]
	v_lshl_add_u64 v[12:13], v[4:5], 0, v[12:13]
	global_load_dword v12, v[12:13], off
	s_and_b64 vcc, exec, s[0:1]
.LBB0_86:
	v_or_b32_e32 v14, 4, v0
	v_ashrrev_i32_e32 v15, 31, v14
	v_lshlrev_b64 v[14:15], 11, v[14:15]
	v_lshl_add_u64 v[14:15], v[4:5], 0, v[14:15]
	global_load_dword v13, v[14:15], off
	s_and_b64 vcc, exec, s[0:1]
.LBB0_88:
	v_or_b32_e32 v14, 5, v0
	v_ashrrev_i32_e32 v15, 31, v14
	v_lshlrev_b64 v[14:15], 11, v[14:15]
	v_lshl_add_u64 v[14:15], v[4:5], 0, v[14:15]
	global_load_dword v14, v[14:15], off
	s_and_b64 vcc, exec, s[0:1]
.LBB0_90:
	v_or_b32_e32 v16, 6, v0
	v_ashrrev_i32_e32 v17, 31, v16
	v_lshlrev_b64 v[16:17], 11, v[16:17]
	v_lshl_add_u64 v[16:17], v[4:5], 0, v[16:17]
	global_load_dword v15, v[16:17], off
	s_and_b64 vcc, exec, s[0:1]
.LBB0_92:
	v_or_b32_e32 v16, 7, v0
	v_ashrrev_i32_e32 v17, 31, v16
	v_lshlrev_b64 v[16:17], 11, v[16:17]
	v_lshl_add_u64 v[4:5], v[4:5], 0, v[16:17]
	global_load_dword v4, v[4:5], off
	s_and_b64 vcc, exec, s[0:1]
	s_cbranch_vccnz .LBB0_77
	global_load_dwordx4 v[30:33], v[6:7], off
	global_load_dwordx4 v[34:37], v[6:7], off offset:16
	s_waitcnt vmcnt(0)
	v_mul_f32_e32 v9, v9, v30
	v_mul_f32_e32 v10, v10, v31
	v_mul_f32_e32 v11, v11, v32
	v_mul_f32_e32 v12, v12, v33
	v_mul_f32_e32 v13, v13, v34
	v_mul_f32_e32 v14, v14, v35
	v_mul_f32_e32 v15, v15, v36
	v_mul_f32_e32 v4, v4, v37
	s_branch .LBB0_77

.Lcp1_entry:
	v_readfirstlane_b32 s0, v192
	v_lshlrev_b32_e32 v16, 4, v192
	s_add_u32 s4, s38, 0xc7b7100
	s_addc_u32 s5, s39, 0
	s_add_u32 s6, s38, 0xc7b7200
	s_addc_u32 s7, s39, 0
	s_lshr_b32 s0, s0, 6
	s_mov_b32 s1, 0
	v_mov_b32_e32 v93, 0
	v_mov_b32_e32 v94, 1
	v_mov_b32_e32 v95, 16
	v_mov_b32_e32 v96, 20
	v_add_u32_e32 v17, 0x2000, v16
	v_add_u32_e32 v18, 0x4000, v16
	v_add_u32_e32 v19, 0x6000, v16
	v_add_u32_e32 v20, 0x8000, v16
	v_add_u32_e32 v21, 0xa000, v16
	v_add_u32_e32 v22, 0xc000, v16
	v_add_u32_e32 v23, 0xe000, v16
	v_add_u32_e32 v104, 0x10000, v16
	v_add_u32_e32 v105, 0x12000, v16
	v_add_u32_e32 v106, 0x14000, v16
	v_add_u32_e32 v107, 0x16000, v16
	v_add_u32_e32 v108, 0x18000, v16
	v_add_u32_e32 v109, 0x1a000, v16
	v_add_u32_e32 v110, 0x1c000, v16
	v_add_u32_e32 v111, 0x1e000, v16
	s_barrier
	s_cmp_lg_u32 s0, 0
	s_cbranch_scc1 .Lcp1_p0
	s_mov_b64 s[22:23], exec
	s_mov_b64 exec, 1
	v_mov_b32_e32 v117, 2
	global_atomic_add v117, v93, v117, s[4:5] sc0
	s_waitcnt vmcnt(0)
	ds_write_b32 v96, v117
	s_waitcnt lgkmcnt(0)
	s_mov_b64 exec, s[22:23]
.Lcp1_p0:
	s_barrier
	ds_read_b32 v119, v96
	s_waitcnt lgkmcnt(0)
	v_readfirstlane_b32 s16, v119
	s_add_u32 s17, s16, 1
	s_cmpk_ge_u32 s16, 0xa80
	s_cbranch_scc1 .Lcp1_exit
	s_cmpk_lt_u32 s16, 0x800
	s_cbranch_scc1 .Lcp1_ac_pro_g2
	s_cmpk_lt_u32 s16, 0xa00
	s_cbranch_scc1 .Lcp1_ac_pro_g1
	s_sub_u32 s18, s16, 0xa00
	s_mov_b32 s8, s80
	s_mov_b32 s9, s81
	s_mov_b32 s19, 0x4a40000
	s_mov_b32 s24, 0x1c000
	s_branch .Lcp1_ac_pro_j
.Lcp1_ac_pro_g1:
	s_sub_u32 s18, s16, 0x800
	s_mov_b32 s8, s82
	s_mov_b32 s9, s83
	s_mov_b32 s19, 0x5a40000
	s_and_b32 s24, s18, 3
	s_cmp_eq_u32 s24, 3
	s_mov_b32 s24, 0x1e000
	s_cselect_b32 s24, 0x1c000, s24
	s_branch .Lcp1_ac_pro_j
.Lcp1_ac_pro_g2:
	s_mov_b32 s18, s16
	s_mov_b32 s8, s84
	s_mov_b32 s9, s85
	s_mov_b32 s19, 0x9a40000
	s_and_b32 s24, s16, 15
	s_cmp_eq_u32 s24, 15
	s_mov_b32 s24, 0x1e000
	s_cselect_b32 s24, 0x1c000, s24
.Lcp1_ac_pro_j:
	s_lshl_b32 s18, s18, 17
	v_add_u32_e32 v91, s24, v16
	s_add_u32 s10, s36, s19
	s_addc_u32 s11, s37, 0
	s_add_u32 s10, s10, s18
	s_addc_u32 s11, s11, 0
	s_add_u32 s8, s8, s18
	s_addc_u32 s9, s9, 0
	s_add_u32 s8, s8, 0x2000
	s_addc_u32 s9, s9, 0
	global_load_dwordx4 v[30:33], v16, s[8:9] nt
	global_load_dwordx4 v[34:37], v17, s[8:9] nt
	global_load_dwordx4 v[38:41], v18, s[8:9] nt
	global_load_dwordx4 v[42:45], v19, s[8:9] nt
	global_load_dwordx4 v[46:49], v20, s[8:9] nt
	global_load_dwordx4 v[50:53], v21, s[8:9] nt
	global_load_dwordx4 v[54:57], v22, s[8:9] nt
	global_load_dwordx4 v[58:61], v23, s[8:9] nt
	global_load_dwordx4 v[62:65], v104, s[8:9] nt
	global_load_dwordx4 v[66:69], v105, s[8:9] nt
	global_load_dwordx4 v[70:73], v106, s[8:9] nt
	global_load_dwordx4 v[74:77], v107, s[8:9] nt
	global_load_dwordx4 v[164:167], v108, s[8:9] nt
	global_load_dwordx4 v[168:171], v109, s[8:9] nt
	global_load_dwordx4 v[172:175], v110, s[8:9] nt
	global_load_dwordx4 v[176:179], v91, s[8:9] nt
.Lcp1_A_loop:
	s_cmp_lg_u32 s0, 0
	s_cbranch_scc1 .Lcp1_A_s1
	s_cmp_lg_u32 s1, 0
	s_cbranch_scc1 .Lcp1_A_s1
	s_mov_b64 s[22:23], exec
	s_mov_b64 exec, 1
	global_load_dword v118, v93, s[6:7] sc1
	global_atomic_add v117, v93, v94, s[4:5] sc0
	s_mov_b64 exec, s[22:23]
.Lcp1_A_s1:
	s_cmpk_ge_u32 s17, 0xa80
	s_cbranch_scc1 .Lcp1_A_tail
	s_cmpk_lt_u32 s17, 0x800
	s_cbranch_scc1 .Lcp1_ac_A_g2
	s_cmpk_lt_u32 s17, 0xa00
	s_cbranch_scc1 .Lcp1_ac_A_g1
	s_sub_u32 s18, s17, 0xa00
	s_mov_b32 s12, s80
	s_mov_b32 s13, s81
	s_mov_b32 s19, 0x4a40000
	s_mov_b32 s24, 0x1c000
	s_branch .Lcp1_ac_A_j
.Lcp1_ac_A_g1:
	s_sub_u32 s18, s17, 0x800
	s_mov_b32 s12, s82
	s_mov_b32 s13, s83
	s_mov_b32 s19, 0x5a40000
	s_and_b32 s24, s18, 3
	s_cmp_eq_u32 s24, 3
	s_mov_b32 s24, 0x1e000
	s_cselect_b32 s24, 0x1c000, s24
	s_branch .Lcp1_ac_A_j
.Lcp1_ac_A_g2:
	s_mov_b32 s18, s17
	s_mov_b32 s12, s84
	s_mov_b32 s13, s85
	s_mov_b32 s19, 0x9a40000
	s_and_b32 s24, s17, 15
	s_cmp_eq_u32 s24, 15
	s_mov_b32 s24, 0x1e000
	s_cselect_b32 s24, 0x1c000, s24
.Lcp1_ac_A_j:
	s_lshl_b32 s18, s18, 17
	v_add_u32_e32 v92, s24, v16
	s_add_u32 s14, s36, s19
	s_addc_u32 s15, s37, 0
	s_add_u32 s14, s14, s18
	s_addc_u32 s15, s15, 0
	s_add_u32 s12, s12, s18
	s_addc_u32 s13, s13, 0
	s_add_u32 s12, s12, 0x2000
	s_addc_u32 s13, s13, 0
	global_load_dwordx4 v[180:183], v16, s[12:13] nt
	global_load_dwordx4 v[184:187], v17, s[12:13] nt
	global_load_dwordx4 v[188:191], v18, s[12:13] nt
	global_load_dwordx4 v[196:199], v19, s[12:13] nt
	global_load_dwordx4 v[200:203], v20, s[12:13] nt
	global_load_dwordx4 v[204:207], v21, s[12:13] nt
	global_load_dwordx4 v[208:211], v22, s[12:13] nt
	global_load_dwordx4 v[212:215], v23, s[12:13] nt
	global_load_dwordx4 v[216:219], v104, s[12:13] nt
	global_load_dwordx4 v[220:223], v105, s[12:13] nt
	global_load_dwordx4 v[224:227], v106, s[12:13] nt
	global_load_dwordx4 v[228:231], v107, s[12:13] nt
	global_load_dwordx4 v[244:247], v108, s[12:13] nt
	global_load_dwordx4 v[248:251], v109, s[12:13] nt
	global_load_dwordx4 v[4:7], v110, s[12:13] nt
	global_load_dwordx4 v[8:11], v92, s[12:13] nt
	s_waitcnt vmcnt(31)
	global_store_dwordx4 v16, v[30:33], s[10:11] nt
	s_waitcnt vmcnt(31)
	global_store_dwordx4 v17, v[34:37], s[10:11] nt
	s_waitcnt vmcnt(31)
	global_store_dwordx4 v18, v[38:41], s[10:11] nt
	s_waitcnt vmcnt(31)
	global_store_dwordx4 v19, v[42:45], s[10:11] nt
	s_waitcnt vmcnt(31)
	global_store_dwordx4 v20, v[46:49], s[10:11] nt
	s_waitcnt vmcnt(31)
	global_store_dwordx4 v21, v[50:53], s[10:11] nt
	s_waitcnt vmcnt(31)
	global_store_dwordx4 v22, v[54:57], s[10:11] nt
	s_waitcnt vmcnt(31)
	global_store_dwordx4 v23, v[58:61], s[10:11] nt
	s_waitcnt vmcnt(31)
	global_store_dwordx4 v104, v[62:65], s[10:11] nt
	s_waitcnt vmcnt(31)
	global_store_dwordx4 v105, v[66:69], s[10:11] nt
	s_waitcnt vmcnt(31)
	global_store_dwordx4 v106, v[70:73], s[10:11] nt
	s_waitcnt vmcnt(31)
	global_store_dwordx4 v107, v[74:77], s[10:11] nt
	s_waitcnt vmcnt(31)
	global_store_dwordx4 v108, v[164:167], s[10:11] nt
	s_waitcnt vmcnt(31)
	global_store_dwordx4 v109, v[168:171], s[10:11] nt
	s_waitcnt vmcnt(31)
	global_store_dwordx4 v110, v[172:175], s[10:11] nt
	s_waitcnt vmcnt(31)
	global_store_dwordx4 v91, v[176:179], s[10:11] nt
	s_cmp_lg_u32 s0, 0
	s_cbranch_scc1 .Lcp1_A_s4
	s_mov_b64 s[22:23], exec
	s_mov_b64 exec, 1
	s_cmp_lg_u32 s1, 0
	s_cbranch_scc1 .Lcp1_A_s4stop
	s_waitcnt vmcnt(32)
	v_readfirstlane_b32 s25, v118
	s_cmpk_gt_u32 s25, 0x377
	s_cselect_b32 s1, 1, 0
	v_readfirstlane_b32 s26, v117
	s_cmpk_ge_u32 s26, 0xa80
	s_cselect_b32 s27, 1, 0
	s_or_b32 s1, s1, s27
	s_branch .Lcp1_A_s4pub
.Lcp1_A_s4stop:
	v_mov_b32_e32 v117, 0xa80
.Lcp1_A_s4pub:
	ds_write_b32 v95, v117
	s_waitcnt lgkmcnt(0)
	s_mov_b64 exec, s[22:23]
.Lcp1_A_s4:
	s_barrier
	ds_read_b32 v119, v95
	s_mov_b32 s16, s17
	s_waitcnt lgkmcnt(0)
	v_readfirstlane_b32 s17, v119

.Lcp1_B_s1:
	s_cmpk_ge_u32 s17, 0xa80
	s_cbranch_scc1 .Lcp1_B_tail
	s_cmpk_lt_u32 s17, 0x800
	s_cbranch_scc1 .Lcp1_ac_B_g2
	s_cmpk_lt_u32 s17, 0xa00
	s_cbranch_scc1 .Lcp1_ac_B_g1
	s_sub_u32 s18, s17, 0xa00
	s_mov_b32 s8, s80
	s_mov_b32 s9, s81
	s_mov_b32 s19, 0x4a40000
	s_mov_b32 s24, 0x1c000
	s_branch .Lcp1_ac_B_j
.Lcp1_ac_B_g1:
	s_sub_u32 s18, s17, 0x800
	s_mov_b32 s8, s82
	s_mov_b32 s9, s83
	s_mov_b32 s19, 0x5a40000
	s_and_b32 s24, s18, 3
	s_cmp_eq_u32 s24, 3
	s_mov_b32 s24, 0x1e000
	s_cselect_b32 s24, 0x1c000, s24
	s_branch .Lcp1_ac_B_j
.Lcp1_ac_B_g2:
	s_mov_b32 s18, s17
	s_mov_b32 s8, s84
	s_mov_b32 s9, s85
	s_mov_b32 s19, 0x9a40000
	s_and_b32 s24, s17, 15
	s_cmp_eq_u32 s24, 15
	s_mov_b32 s24, 0x1e000
	s_cselect_b32 s24, 0x1c000, s24
.Lcp1_ac_B_j:
	s_lshl_b32 s18, s18, 17
	v_add_u32_e32 v91, s24, v16
	s_add_u32 s10, s36, s19
	s_addc_u32 s11, s37, 0
	s_add_u32 s10, s10, s18
	s_addc_u32 s11, s11, 0
	s_add_u32 s8, s8, s18
	s_addc_u32 s9, s9, 0
	s_add_u32 s8, s8, 0x2000
	s_addc_u32 s9, s9, 0
	global_load_dwordx4 v[30:33], v16, s[8:9] nt
	global_load_dwordx4 v[34:37], v17, s[8:9] nt
	global_load_dwordx4 v[38:41], v18, s[8:9] nt
	global_load_dwordx4 v[42:45], v19, s[8:9] nt
	global_load_dwordx4 v[46:49], v20, s[8:9] nt
	global_load_dwordx4 v[50:53], v21, s[8:9] nt
	global_load_dwordx4 v[54:57], v22, s[8:9] nt
	global_load_dwordx4 v[58:61], v23, s[8:9] nt
	global_load_dwordx4 v[62:65], v104, s[8:9] nt
	global_load_dwordx4 v[66:69], v105, s[8:9] nt
	global_load_dwordx4 v[70:73], v106, s[8:9] nt
	global_load_dwordx4 v[74:77], v107, s[8:9] nt
	global_load_dwordx4 v[164:167], v108, s[8:9] nt
	global_load_dwordx4 v[168:171], v109, s[8:9] nt
	global_load_dwordx4 v[172:175], v110, s[8:9] nt
	global_load_dwordx4 v[176:179], v91, s[8:9] nt
	s_waitcnt vmcnt(31)
	global_store_dwordx4 v16, v[180:183], s[14:15] nt
	s_waitcnt vmcnt(31)
	global_store_dwordx4 v17, v[184:187], s[14:15] nt
	s_waitcnt vmcnt(31)
	global_store_dwordx4 v18, v[188:191], s[14:15] nt
	s_waitcnt vmcnt(31)
	global_store_dwordx4 v19, v[196:199], s[14:15] nt
	s_waitcnt vmcnt(31)
	global_store_dwordx4 v20, v[200:203], s[14:15] nt
	s_waitcnt vmcnt(31)
	global_store_dwordx4 v21, v[204:207], s[14:15] nt
	s_waitcnt vmcnt(31)
	global_store_dwordx4 v22, v[208:211], s[14:15] nt
	s_waitcnt vmcnt(31)
	global_store_dwordx4 v23, v[212:215], s[14:15] nt
	s_waitcnt vmcnt(31)
	global_store_dwordx4 v104, v[216:219], s[14:15] nt
	s_waitcnt vmcnt(31)
	global_store_dwordx4 v105, v[220:223], s[14:15] nt
	s_waitcnt vmcnt(31)
	global_store_dwordx4 v106, v[224:227], s[14:15] nt
	s_waitcnt vmcnt(31)
	global_store_dwordx4 v107, v[228:231], s[14:15] nt
	s_waitcnt vmcnt(31)
	global_store_dwordx4 v108, v[244:247], s[14:15] nt
	s_waitcnt vmcnt(31)
	global_store_dwordx4 v109, v[248:251], s[14:15] nt
	s_waitcnt vmcnt(31)
	global_store_dwordx4 v110, v[4:7], s[14:15] nt
	s_waitcnt vmcnt(31)
	global_store_dwordx4 v92, v[8:11], s[14:15] nt
	s_cmp_lg_u32 s0, 0
	s_cbranch_scc1 .Lcp1_B_s4
	s_mov_b64 s[22:23], exec
	s_mov_b64 exec, 1
	s_cmp_lg_u32 s1, 0
	s_cbranch_scc1 .Lcp1_B_s4stop
	s_waitcnt vmcnt(32)
	v_readfirstlane_b32 s25, v118
	s_cmpk_gt_u32 s25, 0x377
	s_cselect_b32 s1, 1, 0
	v_readfirstlane_b32 s26, v117
	s_cmpk_ge_u32 s26, 0xa80
	s_cselect_b32 s27, 1, 0
	s_or_b32 s1, s1, s27
	s_branch .Lcp1_B_s4pub

.Lcp1_B_s4pub:
	ds_write_b32 v96, v117
	s_waitcnt lgkmcnt(0)
	s_mov_b64 exec, s[22:23]
.Lcp1_B_s4:
	s_barrier
	ds_read_b32 v119, v96
	s_mov_b32 s16, s17
	s_waitcnt lgkmcnt(0)
	v_readfirstlane_b32 s17, v119
	s_branch .Lcp1_A_loop
.Lcp1_A_tail:
	s_waitcnt vmcnt(0)
	global_store_dwordx4 v16, v[30:33], s[10:11] nt
	global_store_dwordx4 v17, v[34:37], s[10:11] nt
	global_store_dwordx4 v18, v[38:41], s[10:11] nt
	global_store_dwordx4 v19, v[42:45], s[10:11] nt
	global_store_dwordx4 v20, v[46:49], s[10:11] nt
	global_store_dwordx4 v21, v[50:53], s[10:11] nt
	global_store_dwordx4 v22, v[54:57], s[10:11] nt
	global_store_dwordx4 v23, v[58:61], s[10:11] nt
	global_store_dwordx4 v104, v[62:65], s[10:11] nt
	global_store_dwordx4 v105, v[66:69], s[10:11] nt
	global_store_dwordx4 v106, v[70:73], s[10:11] nt
	global_store_dwordx4 v107, v[74:77], s[10:11] nt
	global_store_dwordx4 v108, v[164:167], s[10:11] nt
	global_store_dwordx4 v109, v[168:171], s[10:11] nt
	global_store_dwordx4 v110, v[172:175], s[10:11] nt
	global_store_dwordx4 v91, v[176:179], s[10:11] nt
	s_branch .Lcp1_exit
.Lcp1_B_tail:
	s_waitcnt vmcnt(0)
	global_store_dwordx4 v16, v[180:183], s[14:15] nt
	global_store_dwordx4 v17, v[184:187], s[14:15] nt
	global_store_dwordx4 v18, v[188:191], s[14:15] nt
	global_store_dwordx4 v19, v[196:199], s[14:15] nt
	global_store_dwordx4 v20, v[200:203], s[14:15] nt
	global_store_dwordx4 v21, v[204:207], s[14:15] nt
	global_store_dwordx4 v22, v[208:211], s[14:15] nt
	global_store_dwordx4 v23, v[212:215], s[14:15] nt
	global_store_dwordx4 v104, v[216:219], s[14:15] nt
	global_store_dwordx4 v105, v[220:223], s[14:15] nt
	global_store_dwordx4 v106, v[224:227], s[14:15] nt
	global_store_dwordx4 v107, v[228:231], s[14:15] nt
	global_store_dwordx4 v108, v[244:247], s[14:15] nt
	global_store_dwordx4 v109, v[248:251], s[14:15] nt
	global_store_dwordx4 v110, v[4:7], s[14:15] nt
	global_store_dwordx4 v92, v[8:11], s[14:15] nt
	s_branch .Lcp1_exit
.Lcp1_exit:
	s_mov_b64 s[0:1], 0
	s_branch .LBB0_200

.LBB0_1154:
	s_or_b64 exec, exec, s[0:1]
	s_min_i32 s3, s3, 0x88
	s_cmp_ge_i32 s2, s3
	s_mov_b64 s[0:1], -1
	s_waitcnt lgkmcnt(0)
	s_barrier
	s_barrier
	s_cbranch_scc0 .LBB0_1178
	s_branch .Lcpd_entry

.LBB0_1193:
.Lcpd_entry:
	v_readfirstlane_b32 s0, v192
	v_lshlrev_b32_e32 v16, 4, v192
	s_add_u32 s4, s38, 0xc7b7100
	s_addc_u32 s5, s39, 0
	s_add_u32 s6, s38, 0xc7b7200
	s_addc_u32 s7, s39, 0
	s_lshr_b32 s0, s0, 6
	s_mov_b32 s1, 0
	v_mov_b32_e32 v93, 0
	v_mov_b32_e32 v94, 1
	v_mov_b32_e32 v95, 16
	v_mov_b32_e32 v96, 20
	v_add_u32_e32 v17, 0x2000, v16
	v_add_u32_e32 v18, 0x4000, v16
	v_add_u32_e32 v19, 0x6000, v16
	v_add_u32_e32 v20, 0x8000, v16
	v_add_u32_e32 v21, 0xa000, v16
	v_add_u32_e32 v22, 0xc000, v16
	v_add_u32_e32 v23, 0xe000, v16
	v_add_u32_e32 v104, 0x10000, v16
	v_add_u32_e32 v105, 0x12000, v16
	v_add_u32_e32 v106, 0x14000, v16
	v_add_u32_e32 v107, 0x16000, v16
	v_add_u32_e32 v108, 0x18000, v16
	v_add_u32_e32 v109, 0x1a000, v16
	v_add_u32_e32 v110, 0x1c000, v16
	v_add_u32_e32 v111, 0x1e000, v16
	s_barrier
	s_cmp_lg_u32 s0, 0
	s_cbranch_scc1 .Lcpd_p0
	s_mov_b64 s[22:23], exec
	s_mov_b64 exec, 1
	v_mov_b32_e32 v117, 2
	global_atomic_add v117, v93, v117, s[4:5] sc0
	s_waitcnt vmcnt(0)
	ds_write_b32 v96, v117
	s_waitcnt lgkmcnt(0)
	s_mov_b64 exec, s[22:23]

.Lcpd_A_loop:
	s_cmp_lg_u32 s0, 0
	s_cbranch_scc1 .Lcpd_A_s1
	s_cmp_lg_u32 s1, 0
	s_cbranch_scc1 .Lcpd_A_s1
	s_mov_b64 s[22:23], exec
	s_mov_b64 exec, 1
	global_atomic_add v117, v93, v94, s[4:5] sc0
	s_mov_b64 exec, s[22:23]

.Lcpd_ac_A_j:
	s_lshl_b32 s18, s18, 17
	v_add_u32_e32 v92, s24, v16
	s_add_u32 s14, s36, s19
	s_addc_u32 s15, s37, 0
	s_add_u32 s14, s14, s18
	s_addc_u32 s15, s15, 0
	s_add_u32 s12, s12, s18
	s_addc_u32 s13, s13, 0
	s_add_u32 s12, s12, 0x2000
	s_addc_u32 s13, s13, 0
	global_load_dwordx4 v[180:183], v16, s[12:13] nt
	global_load_dwordx4 v[184:187], v17, s[12:13] nt
	global_load_dwordx4 v[188:191], v18, s[12:13] nt
	global_load_dwordx4 v[196:199], v19, s[12:13] nt
	global_load_dwordx4 v[200:203], v20, s[12:13] nt
	global_load_dwordx4 v[204:207], v21, s[12:13] nt
	global_load_dwordx4 v[208:211], v22, s[12:13] nt
	global_load_dwordx4 v[212:215], v23, s[12:13] nt
	global_load_dwordx4 v[216:219], v104, s[12:13] nt
	global_load_dwordx4 v[220:223], v105, s[12:13] nt
	global_load_dwordx4 v[224:227], v106, s[12:13] nt
	global_load_dwordx4 v[228:231], v107, s[12:13] nt
	global_load_dwordx4 v[244:247], v108, s[12:13] nt
	global_load_dwordx4 v[248:251], v109, s[12:13] nt
	global_load_dwordx4 v[4:7], v110, s[12:13] nt
	global_load_dwordx4 v[8:11], v92, s[12:13] nt
	s_waitcnt vmcnt(31)
	global_store_dwordx4 v16, v[30:33], s[10:11] nt
	s_waitcnt vmcnt(31)
	global_store_dwordx4 v17, v[34:37], s[10:11] nt
	s_waitcnt vmcnt(31)
	global_store_dwordx4 v18, v[38:41], s[10:11] nt
	s_waitcnt vmcnt(31)
	global_store_dwordx4 v19, v[42:45], s[10:11] nt
	s_waitcnt vmcnt(31)
	global_store_dwordx4 v20, v[46:49], s[10:11] nt
	s_waitcnt vmcnt(31)
	global_store_dwordx4 v21, v[50:53], s[10:11] nt
	s_waitcnt vmcnt(31)
	global_store_dwordx4 v22, v[54:57], s[10:11] nt
	s_waitcnt vmcnt(31)
	global_store_dwordx4 v23, v[58:61], s[10:11] nt
	s_waitcnt vmcnt(31)
	global_store_dwordx4 v104, v[62:65], s[10:11] nt
	s_waitcnt vmcnt(31)
	global_store_dwordx4 v105, v[66:69], s[10:11] nt
	s_waitcnt vmcnt(31)
	global_store_dwordx4 v106, v[70:73], s[10:11] nt
	s_waitcnt vmcnt(31)
	global_store_dwordx4 v107, v[74:77], s[10:11] nt
	s_waitcnt vmcnt(31)
	global_store_dwordx4 v108, v[164:167], s[10:11] nt
	s_waitcnt vmcnt(31)
	global_store_dwordx4 v109, v[168:171], s[10:11] nt
	s_waitcnt vmcnt(31)
	global_store_dwordx4 v110, v[172:175], s[10:11] nt
	s_waitcnt vmcnt(31)
	global_store_dwordx4 v91, v[176:179], s[10:11] nt
	s_cmp_lg_u32 s0, 0
	s_cbranch_scc1 .Lcpd_A_s4
	s_mov_b64 s[22:23], exec
	s_mov_b64 exec, 1
	s_cmp_lg_u32 s1, 0
	s_cbranch_scc1 .Lcpd_A_s4stop
	s_waitcnt vmcnt(32)
	v_readfirstlane_b32 s26, v117
	s_cmpk_ge_u32 s26, 0xa80
	s_cselect_b32 s27, 1, 0
	s_or_b32 s1, s1, s27
	s_branch .Lcpd_A_s4pub

.Lcpd_ac_B_j:
	s_lshl_b32 s18, s18, 17
	v_add_u32_e32 v91, s24, v16
	s_add_u32 s10, s36, s19
	s_addc_u32 s11, s37, 0
	s_add_u32 s10, s10, s18
	s_addc_u32 s11, s11, 0
	s_add_u32 s8, s8, s18
	s_addc_u32 s9, s9, 0
	s_add_u32 s8, s8, 0x2000
	s_addc_u32 s9, s9, 0
	global_load_dwordx4 v[30:33], v16, s[8:9] nt
	global_load_dwordx4 v[34:37], v17, s[8:9] nt
	global_load_dwordx4 v[38:41], v18, s[8:9] nt
	global_load_dwordx4 v[42:45], v19, s[8:9] nt
	global_load_dwordx4 v[46:49], v20, s[8:9] nt
	global_load_dwordx4 v[50:53], v21, s[8:9] nt
	global_load_dwordx4 v[54:57], v22, s[8:9] nt
	global_load_dwordx4 v[58:61], v23, s[8:9] nt
	global_load_dwordx4 v[62:65], v104, s[8:9] nt
	global_load_dwordx4 v[66:69], v105, s[8:9] nt
	global_load_dwordx4 v[70:73], v106, s[8:9] nt
	global_load_dwordx4 v[74:77], v107, s[8:9] nt
	global_load_dwordx4 v[164:167], v108, s[8:9] nt
	global_load_dwordx4 v[168:171], v109, s[8:9] nt
	global_load_dwordx4 v[172:175], v110, s[8:9] nt
	global_load_dwordx4 v[176:179], v91, s[8:9] nt
	s_waitcnt vmcnt(31)
	global_store_dwordx4 v16, v[180:183], s[14:15] nt
	s_waitcnt vmcnt(31)
	global_store_dwordx4 v17, v[184:187], s[14:15] nt
	s_waitcnt vmcnt(31)
	global_store_dwordx4 v18, v[188:191], s[14:15] nt
	s_waitcnt vmcnt(31)
	global_store_dwordx4 v19, v[196:199], s[14:15] nt
	s_waitcnt vmcnt(31)
	global_store_dwordx4 v20, v[200:203], s[14:15] nt
	s_waitcnt vmcnt(31)
	global_store_dwordx4 v21, v[204:207], s[14:15] nt
	s_waitcnt vmcnt(31)
	global_store_dwordx4 v22, v[208:211], s[14:15] nt
	s_waitcnt vmcnt(31)
	global_store_dwordx4 v23, v[212:215], s[14:15] nt
	s_waitcnt vmcnt(31)
	global_store_dwordx4 v104, v[216:219], s[14:15] nt
	s_waitcnt vmcnt(31)
	global_store_dwordx4 v105, v[220:223], s[14:15] nt
	s_waitcnt vmcnt(31)
	global_store_dwordx4 v106, v[224:227], s[14:15] nt
	s_waitcnt vmcnt(31)
	global_store_dwordx4 v107, v[228:231], s[14:15] nt
	s_waitcnt vmcnt(31)
	global_store_dwordx4 v108, v[244:247], s[14:15] nt
	s_waitcnt vmcnt(31)
	global_store_dwordx4 v109, v[248:251], s[14:15] nt
	s_waitcnt vmcnt(31)
	global_store_dwordx4 v110, v[4:7], s[14:15] nt
	s_waitcnt vmcnt(31)
	global_store_dwordx4 v92, v[8:11], s[14:15] nt
	s_cmp_lg_u32 s0, 0
	s_cbranch_scc1 .Lcpd_B_s4
	s_mov_b64 s[22:23], exec
	s_mov_b64 exec, 1
	s_cmp_lg_u32 s1, 0
	s_cbranch_scc1 .Lcpd_B_s4stop
	s_waitcnt vmcnt(32)
	v_readfirstlane_b32 s26, v117
	s_cmpk_ge_u32 s26, 0xa80
	s_cselect_b32 s27, 1, 0
	s_or_b32 s1, s1, s27
	s_branch .Lcpd_B_s4pub

.Lcpd_exit:
	s_branch .LBB0_1213
